# combine MFMA block staggered between wave halves (waves 4-7 run it inside the first i0 iteration)
# baseline (speedup 1.0000x reference)
; __device__ void phase_combine(const P& p, int l, int ntok, float* lds) {
;     ...
;         float gate[4];
; #pragma unroll
;         for (int i = 0; i < 4; ++i) gate[i] = 0.f;
; #pragma unroll
;         for (int m = 0; m < 96; m += 4) {
; #pragma unroll
;           for (int i = 0; i < 4; ++i) {
;             float4 s = *reinterpret_cast<const float4*>(sig + (i0 + i) * 96 + m);
;             gate[i] += s.x * g2r[m] + s.y * g2r[m + 1] + s.z * g2r[m + 2] + s.w * g2r[m + 3];
;           }
;         }
.LBB0_93:
	s_or_b64 exec, exec, s[0:1]
	s_cmpk_lt_i32 s55, 0x400
	s_movk_i32 s0, 0xfff
	s_cselect_b32 s57, s0, 0xff
	v_readlane_b32 s34, v240, 12
	v_readlane_b32 s62, v240, 14
	s_cselect_b32 s58, 63, 0xff
	s_and_b32 s59, s57, s56
	s_mov_b32 s60, 0
	v_readlane_b32 s35, v240, 13
	v_readlane_b32 s63, v240, 15
	s_mov_b32 s33, 0x800000
	s_movk_i32 s61, 0x3600
	s_mov_b32 s66, 0x88000
	s_mov_b64 s[68:69], 0x3040
	s_waitcnt lgkmcnt(0)
	s_barrier
	v_readfirstlane_b32 s98, v168
	s_lshr_b32 s98, s98, 6
	s_cmp_lt_u32 s98, 4
	s_cbranch_scc0 .Lmf_skip1
	v_and_b32_e32 v241, 15, v168
	v_bfe_u32 v242, v168, 4, 2
	v_mul_u32_u24_e32 v241, 0x180, v241
	v_mul_u32_u24_e32 v243, 0x1fc0, v242
	v_lshl_add_u32 v241, v242, 2, v241
	v_lshl_add_u32 v243, v168, 2, v243
	ds_read_b32 v244, v241
	ds_read_b32 v245, v241 offset:16
	ds_read_b32 v246, v241 offset:32
	ds_read_b32 v247, v241 offset:48
	ds_read_b32 v248, v241 offset:64
	ds_read_b32 v249, v241 offset:80
	ds_read_b32 v250, v241 offset:96
	ds_read_b32 v251, v241 offset:112
	ds_read_b32 v252, v241 offset:128
	ds_read_b32 v253, v241 offset:144
	ds_read_b32 v254, v241 offset:160
	ds_read_b32 v255, v241 offset:176
	s_waitcnt lgkmcnt(0)
	v_mfma_f32_16x16x4_f32 v[220:223], v244, v90, 0
	v_mfma_f32_16x16x4_f32 v[220:223], v245, v33, v[220:223]
	v_mfma_f32_16x16x4_f32 v[220:223], v246, v80, v[220:223]
	v_mfma_f32_16x16x4_f32 v[220:223], v247, v83, v[220:223]
	v_mfma_f32_16x16x4_f32 v[220:223], v248, v86, v[220:223]
	v_mfma_f32_16x16x4_f32 v[220:223], v249, v89, v[220:223]
	v_mfma_f32_16x16x4_f32 v[220:223], v250, v25, v[220:223]
	v_mfma_f32_16x16x4_f32 v[220:223], v251, v96, v[220:223]
	v_mfma_f32_16x16x4_f32 v[220:223], v252, v97, v[220:223]
	v_mfma_f32_16x16x4_f32 v[220:223], v253, v98, v[220:223]
	v_mfma_f32_16x16x4_f32 v[220:223], v254, v99, v[220:223]
	v_mfma_f32_16x16x4_f32 v[220:223], v255, v100, v[220:223]
	v_mfma_f32_16x16x4_f32 v[224:227], v244, v91, 0
	v_mfma_f32_16x16x4_f32 v[224:227], v245, v78, v[224:227]
	v_mfma_f32_16x16x4_f32 v[224:227], v246, v81, v[224:227]
	v_mfma_f32_16x16x4_f32 v[224:227], v247, v84, v[224:227]
	v_mfma_f32_16x16x4_f32 v[224:227], v248, v87, v[224:227]
	v_mfma_f32_16x16x4_f32 v[224:227], v249, v26, v[224:227]
	v_mfma_f32_16x16x4_f32 v[224:227], v250, v30, v[224:227]
	v_mfma_f32_16x16x4_f32 v[224:227], v251, v34, v[224:227]
	v_mfma_f32_16x16x4_f32 v[224:227], v252, v38, v[224:227]
	v_mfma_f32_16x16x4_f32 v[224:227], v253, v42, v[224:227]
	v_mfma_f32_16x16x4_f32 v[224:227], v254, v46, v[224:227]
	v_mfma_f32_16x16x4_f32 v[224:227], v255, v50, v[224:227]
	v_mfma_f32_16x16x4_f32 v[228:231], v244, v32, 0
	v_mfma_f32_16x16x4_f32 v[228:231], v245, v79, v[228:231]
	v_mfma_f32_16x16x4_f32 v[228:231], v246, v82, v[228:231]
	v_mfma_f32_16x16x4_f32 v[228:231], v247, v85, v[228:231]
	v_mfma_f32_16x16x4_f32 v[228:231], v248, v88, v[228:231]
	v_mfma_f32_16x16x4_f32 v[228:231], v249, v27, v[228:231]
	v_mfma_f32_16x16x4_f32 v[228:231], v250, v31, v[228:231]
	v_mfma_f32_16x16x4_f32 v[228:231], v251, v35, v[228:231]
	v_mfma_f32_16x16x4_f32 v[228:231], v252, v39, v[228:231]
	v_mfma_f32_16x16x4_f32 v[228:231], v253, v43, v[228:231]
	v_mfma_f32_16x16x4_f32 v[228:231], v254, v47, v[228:231]
	v_mfma_f32_16x16x4_f32 v[228:231], v255, v51, v[228:231]
	v_mfma_f32_16x16x4_f32 v[232:235], v244, v92, 0
	v_mfma_f32_16x16x4_f32 v[232:235], v245, v93, v[232:235]
	v_mfma_f32_16x16x4_f32 v[232:235], v246, v11, v[232:235]
	v_mfma_f32_16x16x4_f32 v[232:235], v247, v94, v[232:235]
	v_mfma_f32_16x16x4_f32 v[232:235], v248, v95, v[232:235]
	v_mfma_f32_16x16x4_f32 v[232:235], v249, v24, v[232:235]
	v_mfma_f32_16x16x4_f32 v[232:235], v250, v103, v[232:235]
	v_mfma_f32_16x16x4_f32 v[232:235], v251, v28, v[232:235]
	v_mfma_f32_16x16x4_f32 v[232:235], v252, v29, v[232:235]
	v_mfma_f32_16x16x4_f32 v[232:235], v253, v36, v[232:235]
	v_mfma_f32_16x16x4_f32 v[232:235], v254, v37, v[232:235]
	v_mfma_f32_16x16x4_f32 v[232:235], v255, v40, v[232:235]
	ds_read_b32 v244, v241 offset:192
	ds_read_b32 v245, v241 offset:208
	ds_read_b32 v246, v241 offset:224
	ds_read_b32 v247, v241 offset:240
	ds_read_b32 v248, v241 offset:256
	ds_read_b32 v249, v241 offset:272
	ds_read_b32 v250, v241 offset:288
	ds_read_b32 v251, v241 offset:304
	ds_read_b32 v252, v241 offset:320
	ds_read_b32 v253, v241 offset:336
	ds_read_b32 v254, v241 offset:352
	ds_read_b32 v255, v241 offset:368
	s_waitcnt lgkmcnt(0)
; __device__ void phase_combine(const P& p, int l, int ntok, float* lds) {
;     ...
;     for (int i0 = 0; i0 < 16; i0 += 4) {
;       float sf[4], sb[4];
;       unsigned y0[4], y1[4], a0[4], a1[4], a2[4], a3[4], vc[4], vp[4], vn[4], g0r[4], g1r[4], cbr[4], ucc[6], uch[6];
; #pragma unroll
;       for (int i = 0; i < 4; ++i) {
;         int row = r0 + i0 + i, t = tb + i0 + i;
;         y0[i] = or0[(size_t)row * 512 + tid]; y1[i] = or1[(size_t)row * 512 + tid];
;         const u16* pv = p.projb + (size_t)row * PROJP + O_RKV + 1024 + tid;
;         vc[i] = pv[0]; vp[i] = pv[t > 0 ? -PROJP : 0]; vn[i] = pv[t < T - 1 ? PROJP : 0];
;         sf[i] = p.sbon[(size_t)row * 8 + wv]; sb[i] = p.sbon[(size_t)NT * 8 + (size_t)row * 8 + wv];
;         size_t ob = (size_t)row * 512 + hh * 128 + lane;
;         a0[i] = om0[ob]; a1[i] = om1[ob]; a2[i] = om0[ob + 64]; a3[i] = om1[ob + 64];
;         const u16* pg = p.projb + (size_t)row * PROJP + gch;
;         g0r[i] = pg[0]; g1r[i] = pg[64];
;         cbr[i] = p.projb[(size_t)row * PROJP + O_CB + tid];
;       }
;     ...
;         for (int m = 0; m < 96; m += 4) {
; #pragma unroll
;           for (int i = 0; i < 4; ++i) {
;             float4 s = *reinterpret_cast<const float4*>(sig + (i0 + i) * 96 + m);
;             gate[i] += s.x * g2r[m] + s.y * g2r[m + 1] + s.z * g2r[m + 2] + s.w * g2r[m + 3];
;           }
;         }
	v_mfma_f32_16x16x4_f32 v[220:223], v244, v101, v[220:223]
	v_mfma_f32_16x16x4_f32 v[220:223], v245, v102, v[220:223]
	v_mfma_f32_16x16x4_f32 v[220:223], v246, v45, v[220:223]
	v_mfma_f32_16x16x4_f32 v[220:223], v247, v52, v[220:223]
	v_mfma_f32_16x16x4_f32 v[220:223], v248, v59, v[220:223]
	v_mfma_f32_16x16x4_f32 v[220:223], v249, v66, v[220:223]
	v_mfma_f32_16x16x4_f32 v[220:223], v250, v71, v[220:223]
	v_mfma_f32_16x16x4_f32 v[220:223], v251, v104, v[220:223]
	v_mfma_f32_16x16x4_f32 v[220:223], v252, v107, v[220:223]
	v_mfma_f32_16x16x4_f32 v[220:223], v253, v110, v[220:223]
	v_mfma_f32_16x16x4_f32 v[220:223], v254, v76, v[220:223]
	v_mfma_f32_16x16x4_f32 v[220:223], v255, v114, v[220:223]
	v_mfma_f32_16x16x4_f32 v[224:227], v244, v56, v[224:227]
	v_mfma_f32_16x16x4_f32 v[224:227], v245, v60, v[224:227]
	v_mfma_f32_16x16x4_f32 v[224:227], v246, v48, v[224:227]
	v_mfma_f32_16x16x4_f32 v[224:227], v247, v53, v[224:227]
	v_mfma_f32_16x16x4_f32 v[224:227], v248, v64, v[224:227]
	v_mfma_f32_16x16x4_f32 v[224:227], v249, v67, v[224:227]
	v_mfma_f32_16x16x4_f32 v[224:227], v250, v74, v[224:227]
	v_mfma_f32_16x16x4_f32 v[224:227], v251, v105, v[224:227]
	v_mfma_f32_16x16x4_f32 v[224:227], v252, v108, v[224:227]
	v_mfma_f32_16x16x4_f32 v[224:227], v253, v111, v[224:227]
	v_mfma_f32_16x16x4_f32 v[224:227], v254, v77, v[224:227]
	v_mfma_f32_16x16x4_f32 v[224:227], v255, v115, v[224:227]
	v_mfma_f32_16x16x4_f32 v[228:231], v244, v57, v[228:231]
	v_mfma_f32_16x16x4_f32 v[228:231], v245, v61, v[228:231]
	v_mfma_f32_16x16x4_f32 v[228:231], v246, v49, v[228:231]
	v_mfma_f32_16x16x4_f32 v[228:231], v247, v58, v[228:231]
	v_mfma_f32_16x16x4_f32 v[228:231], v248, v65, v[228:231]
	v_mfma_f32_16x16x4_f32 v[228:231], v249, v70, v[228:231]
	v_mfma_f32_16x16x4_f32 v[228:231], v250, v75, v[228:231]
	v_mfma_f32_16x16x4_f32 v[228:231], v251, v106, v[228:231]
	v_mfma_f32_16x16x4_f32 v[228:231], v252, v109, v[228:231]
	v_mfma_f32_16x16x4_f32 v[228:231], v253, v112, v[228:231]
	v_mfma_f32_16x16x4_f32 v[228:231], v254, v113, v[228:231]
	v_mfma_f32_16x16x4_f32 v[228:231], v255, v117, v[228:231]
	v_mfma_f32_16x16x4_f32 v[232:235], v244, v41, v[232:235]
	v_mfma_f32_16x16x4_f32 v[232:235], v245, v44, v[232:235]
	v_mfma_f32_16x16x4_f32 v[232:235], v246, v54, v[232:235]
	v_mfma_f32_16x16x4_f32 v[232:235], v247, v55, v[232:235]
	v_mfma_f32_16x16x4_f32 v[232:235], v248, v62, v[232:235]
	v_mfma_f32_16x16x4_f32 v[232:235], v249, v63, v[232:235]
	v_mfma_f32_16x16x4_f32 v[232:235], v250, v68, v[232:235]
	v_mfma_f32_16x16x4_f32 v[232:235], v251, v69, v[232:235]
	v_mfma_f32_16x16x4_f32 v[232:235], v252, v72, v[232:235]
	v_mfma_f32_16x16x4_f32 v[232:235], v253, v73, v[232:235]
	v_mfma_f32_16x16x4_f32 v[232:235], v254, v116, v[232:235]
	v_mfma_f32_16x16x4_f32 v[232:235], v255, v118, v[232:235]
	s_nop 7
	s_nop 3
	ds_write_b32 v243, v220 offset:8192
	ds_write_b32 v243, v221 offset:10240
	ds_write_b32 v243, v222 offset:12288
	ds_write_b32 v243, v223 offset:14336
	ds_write_b32 v243, v224 offset:8256
	ds_write_b32 v243, v225 offset:10304
	ds_write_b32 v243, v226 offset:12352
	ds_write_b32 v243, v227 offset:14400
	ds_write_b32 v243, v228 offset:8320
	ds_write_b32 v243, v229 offset:10368
	ds_write_b32 v243, v230 offset:12416
	ds_write_b32 v243, v231 offset:14464
	ds_write_b32 v243, v232 offset:8384
	ds_write_b32 v243, v233 offset:10432
	ds_write_b32 v243, v234 offset:12480
	ds_write_b32 v243, v235 offset:14528
	s_waitcnt lgkmcnt(0)
.Lmf_skip1:
.LBB0_94:
	s_or_b32 s46, s60, s56
	s_ashr_i32 s47, s46, 31
	s_lshl_b64 s[0:1], s[46:47], 9
	s_or_b32 s2, s60, s59
	v_lshl_add_u64 v[0:1], s[0:1], 0, v[4:5]
	s_mul_i32 s20, s46, 0x3600
	v_lshlrev_b64 v[0:1], 1, v[0:1]
	s_mul_hi_i32 s3, s46, 0x3600
	s_add_u32 s22, s94, s20
	v_lshl_add_u64 v[2:3], s[34:35], 0, v[0:1]
	v_lshl_add_u64 v[0:1], s[62:63], 0, v[0:1]
	s_addc_u32 s23, s95, s3
	v_lshlrev_b64 v[22:23], 1, v[4:5]
	v_sub_co_u32_e64 v139, s[52:53], s2, 1
	global_load_ushort v201, v[2:3], off
	global_load_ushort v202, v[0:1], off
	v_lshl_add_u64 v[0:1], s[22:23], 0, v[22:23]
	s_and_b64 s[24:25], s[52:53], exec
	v_add_co_u32_e32 v18, vcc, s75, v0
	s_cselect_b32 s25, 0, -1
	s_cselect_b32 s24, 0, 0xffffca00
	s_cmp_lt_u32 s2, s57
	v_lshl_add_u64 v[2:3], v[0:1], 0, s[68:69]
	v_addc_co_u32_e32 v19, vcc, 0, v1, vcc
	s_cselect_b64 s[44:45], -1, 0
	global_load_ushort v199, v[18:19], off offset:64
	v_lshl_add_u64 v[18:19], v[2:3], 0, s[24:25]
	s_and_b64 s[24:25], s[44:45], exec
	s_cselect_b32 s28, 0x3600, 0
	v_lshl_add_u64 v[2:3], v[2:3], 0, s[28:29]
	s_lshl_b64 s[24:25], s[46:47], 5
	global_load_ushort v208, v[18:19], off
	global_load_ushort v210, v[2:3], off
	s_add_u32 s24, s10, s24
	v_mov_b32_e32 v19, s1
	v_or_b32_e32 v18, s0, v10
	s_addc_u32 s25, s11, s25
	v_lshlrev_b64 v[18:19], 1, v[18:19]
	s_or_b32 s50, s46, 1
	v_lshl_add_u64 v[20:21], v[6:7], 0, v[18:19]
	v_lshl_add_u64 v[18:19], v[8:9], 0, v[18:19]
	s_ashr_i32 s51, s50, 31
	global_load_ushort v195, v[20:21], off
	global_load_ushort v193, v[18:19], off
	global_load_ushort v196, v[20:21], off offset:128
	global_load_ushort v194, v[18:19], off offset:128
	global_load_ushort v192, v134, s[22:23]
	global_load_ushort v191, v134, s[22:23] offset:128
	v_add_co_u32_e32 v18, vcc, s96, v0
	s_or_b32 s3, s2, 1
	s_lshl_b64 s[0:1], s[50:51], 9
	s_mul_i32 s22, s50, 0x3600
	v_addc_co_u32_e32 v19, vcc, 0, v1, vcc
	s_mul_hi_i32 s20, s50, 0x3600
	s_add_u32 s22, s94, s22
	global_load_ushort v138, v[18:19], off offset:3136
	v_lshl_add_u64 v[18:19], s[0:1], 0, v[4:5]
	s_addc_u32 s23, s95, s20
	v_lshlrev_b64 v[18:19], 1, v[18:19]
	s_cmp_lt_u32 s3, s57
	v_lshl_add_u64 v[20:21], s[34:35], 0, v[18:19]
; __device__ void phase_combine(const P& p, int l, int ntok, float* lds) {
;     ...
;       for (int i = 0; i < 4; ++i) {
;         int row = r0 + i0 + i, t = tb + i0 + i;
;         y0[i] = or0[(size_t)row * 512 + tid]; y1[i] = or1[(size_t)row * 512 + tid];
;         const u16* pv = p.projb + (size_t)row * PROJP + O_RKV + 1024 + tid;
;         vc[i] = pv[0]; vp[i] = pv[t > 0 ? -PROJP : 0]; vn[i] = pv[t < T - 1 ? PROJP : 0];
;         sf[i] = p.sbon[(size_t)row * 8 + wv]; sb[i] = p.sbon[(size_t)NT * 8 + (size_t)row * 8 + wv];
;         size_t ob = (size_t)row * 512 + hh * 128 + lane;
;         a0[i] = om0[ob]; a1[i] = om1[ob]; a2[i] = om0[ob + 64]; a3[i] = om1[ob + 64];
;         const u16* pg = p.projb + (size_t)row * PROJP + gch;
;         g0r[i] = pg[0]; g1r[i] = pg[64];
;         cbr[i] = p.projb[(size_t)row * PROJP + O_CB + tid];
;       }
;       {
;         const u16* pc = p.projb + (size_t)(r0 + i0) * PROJP;
; #pragma unroll
;         for (int j = 0; j < 6; ++j) {
;           int t = tb + i0 + j - 1;
;           int off = (t < 0 ? 0 : (t > T - 1 ? T - 1 : t)) - (tb + i0);
;           const u16* pr = pc + (long)off * PROJP;
;           ucc[j] = pr[O_CC + tid]; uch[j] = pr[O_CH + tid];
;         }
	v_lshl_add_u64 v[18:19], s[62:63], 0, v[18:19]
	s_cselect_b64 s[42:43], -1, 0
	v_lshl_add_u64 v[2:3], s[24:25], 0, v[16:17]
	global_load_ushort v212, v[20:21], off
	global_load_ushort v213, v[18:19], off
	v_lshl_add_u64 v[20:21], s[22:23], 0, v[22:23]
	s_and_b64 s[24:25], s[42:43], exec
	v_lshl_add_u64 v[18:19], v[20:21], 0, s[68:69]
	v_add_co_u32_e32 v136, vcc, s75, v20
	s_cselect_b32 s28, 0x3600, 0
	s_nop 0
	v_addc_co_u32_e32 v137, vcc, 0, v21, vcc
	v_lshl_add_u64 v[18:19], v[18:19], 0, s[28:29]
	s_lshl_b64 s[24:25], s[50:51], 5
	global_load_ushort v198, v[136:137], off offset:64
	global_load_ushort v206, v[18:19], off
	s_add_u32 s24, s10, s24
	v_mov_b32_e32 v137, s1
	v_or_b32_e32 v136, s0, v10
	s_addc_u32 s25, s11, s25
	v_lshlrev_b64 v[136:137], 1, v[136:137]
	s_or_b32 s48, s46, 2
	v_lshl_add_u64 v[140:141], v[6:7], 0, v[136:137]
	v_lshl_add_u64 v[136:137], v[8:9], 0, v[136:137]
	s_ashr_i32 s49, s48, 31
	global_load_ushort v167, v[140:141], off
	global_load_ushort v165, v[136:137], off
	global_load_ushort v190, v[140:141], off offset:128
	global_load_ushort v166, v[136:137], off offset:128
	global_load_ushort v164, v134, s[22:23]
	global_load_ushort v163, v134, s[22:23] offset:128
	v_add_co_u32_e32 v20, vcc, s96, v20
	s_or_b32 s23, s2, 2
	s_lshl_b64 s[0:1], s[48:49], 9
	s_mul_i32 s22, s48, 0x3600
	v_lshl_add_u64 v[18:19], s[24:25], 0, v[16:17]
	v_addc_co_u32_e32 v21, vcc, 0, v21, vcc
	s_mul_hi_i32 s20, s48, 0x3600
	s_add_u32 s24, s94, s22
	global_load_ushort v137, v[20:21], off offset:3136
	v_lshl_add_u64 v[20:21], s[0:1], 0, v[4:5]
	s_addc_u32 s25, s95, s20
	v_lshlrev_b64 v[20:21], 1, v[20:21]
	s_cmp_lt_u32 s23, s57
	v_lshl_add_u64 v[140:141], s[34:35], 0, v[20:21]
	v_lshl_add_u64 v[20:21], s[62:63], 0, v[20:21]
	s_cselect_b64 s[40:41], -1, 0
	global_load_ushort v209, v[140:141], off
	global_load_ushort v211, v[20:21], off
	v_lshl_add_u64 v[140:141], s[24:25], 0, v[22:23]
	s_and_b64 s[26:27], s[40:41], exec
	v_lshl_add_u64 v[20:21], v[140:141], 0, s[68:69]
	v_add_co_u32_e32 v142, vcc, s75, v140
	s_cselect_b32 s28, 0x3600, 0
	s_lshl_b64 s[26:27], s[48:49], 5
	v_addc_co_u32_e32 v143, vcc, 0, v141, vcc
	v_lshl_add_u64 v[20:21], v[20:21], 0, s[28:29]
	s_add_u32 s26, s10, s26
	global_load_ushort v197, v[142:143], off offset:64
	global_load_ushort v204, v[20:21], off
	s_addc_u32 s27, s11, s27
	v_mov_b32_e32 v143, s1
	v_or_b32_e32 v142, s0, v10
	s_or_b32 s36, s46, 3
	v_lshlrev_b64 v[142:143], 1, v[142:143]
	v_add_co_u32_e32 v140, vcc, s96, v140
	s_ashr_i32 s37, s36, 31
	v_lshl_add_u64 v[144:145], v[6:7], 0, v[142:143]
	v_lshl_add_u64 v[142:143], v[8:9], 0, v[142:143]
	v_addc_co_u32_e32 v141, vcc, 0, v141, vcc
	s_lshl_b64 s[0:1], s[36:37], 9
	v_lshl_add_u64 v[20:21], s[26:27], 0, v[16:17]
	global_load_ushort v161, v[144:145], off
	global_load_ushort v159, v[142:143], off
	global_load_ushort v162, v[144:145], off offset:128
	global_load_ushort v160, v[142:143], off offset:128
	global_load_ushort v158, v134, s[24:25]
	global_load_ushort v157, v134, s[24:25] offset:128
	global_load_ushort v136, v[140:141], off offset:3136
	s_or_b32 s26, s2, 3
	v_lshl_add_u64 v[140:141], s[0:1], 0, v[4:5]
	s_mul_i32 s22, s36, 0x3600
	v_lshlrev_b64 v[140:141], 1, v[140:141]
	s_mul_hi_i32 s20, s36, 0x3600
	s_add_u32 s24, s94, s22
	v_lshl_add_u64 v[142:143], s[34:35], 0, v[140:141]
	v_lshl_add_u64 v[140:141], s[62:63], 0, v[140:141]
	s_addc_u32 s25, s95, s20
	global_load_ushort v205, v[142:143], off
	global_load_ushort v207, v[140:141], off
	v_lshl_add_u64 v[140:141], s[24:25], 0, v[22:23]
	v_add_co_u32_e32 v142, vcc, s75, v140
	s_cmp_lt_u32 s26, s57
	s_nop 0
	v_addc_co_u32_e32 v143, vcc, 0, v141, vcc
	s_cselect_b64 vcc, -1, 0
	s_and_b64 s[30:31], vcc, exec
	v_lshl_add_u64 v[22:23], v[140:141], 0, s[68:69]
	s_cselect_b32 s28, 0x3600, 0
	v_lshl_add_u64 v[22:23], v[22:23], 0, s[28:29]
	global_load_ushort v200, v[142:143], off offset:64
	global_load_ushort v203, v[22:23], off
	v_mov_b32_e32 v143, s1
	v_or_b32_e32 v142, s0, v10
	v_min_i32_e32 v139, s57, v139
	v_lshlrev_b64 v[142:143], 1, v[142:143]
	v_add_co_u32_e64 v140, s[0:1], s96, v140
	v_cndmask_b32_e64 v139, v139, 0, s[52:53]
	v_lshl_add_u64 v[144:145], v[6:7], 0, v[142:143]
	v_lshl_add_u64 v[142:143], v[8:9], 0, v[142:143]
	v_addc_co_u32_e64 v141, s[0:1], 0, v141, s[0:1]
	v_subrev_u32_e32 v139, s2, v139
	global_load_ushort v155, v[144:145], off
	global_load_ushort v153, v[142:143], off
	global_load_ushort v156, v[144:145], off offset:128
	global_load_ushort v154, v[142:143], off offset:128
	global_load_ushort v152, v134, s[24:25]
	global_load_ushort v149, v134, s[24:25] offset:128
	global_load_ushort v135, v[140:141], off offset:3136
	v_mad_i64_i32 v[140:141], s[0:1], v139, s61, v[0:1]
	v_add_co_u32_e64 v140, s[0:1], s78, v140
	s_lshl_b64 s[30:31], s[36:37], 5
	s_nop 0
	v_addc_co_u32_e64 v141, s[0:1], 0, v141, s[0:1]
	global_load_ushort v139, v[140:141], off offset:64
	s_nop 0
	global_load_ushort v140, v[140:141], off offset:1088
	v_mov_b32_e32 v141, s57
	v_sub_u32_e64 v141, s2, v141 clamp
	v_sub_u32_e32 v141, 0, v141
	v_mad_i64_i32 v[142:143], s[0:1], v141, s61, v[0:1]
	v_add_co_u32_e64 v142, s[0:1], s78, v142
	s_add_u32 s30, s10, s30
	s_nop 0
	v_addc_co_u32_e64 v143, s[0:1], 0, v143, s[0:1]
	s_addc_u32 s31, s11, s31
	s_min_u32 s0, s3, s57
	s_sub_i32 s0, s0, s2
	global_load_ushort v147, v[142:143], off offset:64
	global_load_ushort v148, v[142:143], off offset:1088
	v_mad_i64_i32 v[142:143], s[0:1], s0, v179, v[0:1]
	v_add_co_u32_e64 v142, s[0:1], s78, v142
	v_lshl_add_u64 v[22:23], s[30:31], 0, v[16:17]
	s_nop 0
	v_addc_co_u32_e64 v143, s[0:1], 0, v143, s[0:1]
	s_min_u32 s0, s23, s57
	s_sub_i32 s0, s0, s2
	global_load_ushort v150, v[142:143], off offset:64
	global_load_ushort v151, v[142:143], off offset:1088
	v_mad_i64_i32 v[142:143], s[0:1], s0, v179, v[0:1]
	v_add_co_u32_e64 v142, s[0:1], s78, v142
	s_waitcnt vmcnt(25)
; __device__ void phase_combine(const P& p, int l, int ntok, float* lds) {
;     ...
;       for (int i = 0; i < 4; ++i) {
;         int row = r0 + i0 + i, t = tb + i0 + i;
;         y0[i] = or0[(size_t)row * 512 + tid]; y1[i] = or1[(size_t)row * 512 + tid];
;         const u16* pv = p.projb + (size_t)row * PROJP + O_RKV + 1024 + tid;
;         vc[i] = pv[0]; vp[i] = pv[t > 0 ? -PROJP : 0]; vn[i] = pv[t < T - 1 ? PROJP : 0];
;         sf[i] = p.sbon[(size_t)row * 8 + wv]; sb[i] = p.sbon[(size_t)NT * 8 + (size_t)row * 8 + wv];
;         size_t ob = (size_t)row * 512 + hh * 128 + lane;
;         a0[i] = om0[ob]; a1[i] = om1[ob]; a2[i] = om0[ob + 64]; a3[i] = om1[ob + 64];
;         const u16* pg = p.projb + (size_t)row * PROJP + gch;
;         g0r[i] = pg[0]; g1r[i] = pg[64];
;         cbr[i] = p.projb[(size_t)row * PROJP + O_CB + tid];
;       }
;       {
;         const u16* pc = p.projb + (size_t)(r0 + i0) * PROJP;
; #pragma unroll
;         for (int j = 0; j < 6; ++j) {
;           int t = tb + i0 + j - 1;
;           int off = (t < 0 ? 0 : (t > T - 1 ? T - 1 : t)) - (tb + i0);
;           const u16* pr = pc + (long)off * PROJP;
;           ucc[j] = pr[O_CC + tid]; uch[j] = pr[O_CH + tid];
;         }
;     ...
;         for (int m = 0; m < 96; m += 4) {
; #pragma unroll
;           for (int i = 0; i < 4; ++i) {
;             float4 s = *reinterpret_cast<const float4*>(sig + (i0 + i) * 96 + m);
;             gate[i] += s.x * g2r[m] + s.y * g2r[m + 1] + s.z * g2r[m + 2] + s.w * g2r[m + 3];
;           }
;         }
	v_mov_b32_e32 v216, v197
	v_addc_co_u32_e64 v143, s[0:1], 0, v143, s[0:1]
	s_min_u32 s0, s26, s57
	s_sub_i32 s0, s0, s2
	global_load_ushort v145, v[142:143], off offset:64
	global_load_ushort v146, v[142:143], off offset:1088
	v_mad_i64_i32 v[142:143], s[0:1], s0, v179, v[0:1]
	v_add_co_u32_e64 v214, s[0:1], s78, v142
	s_nop 1
	v_addc_co_u32_e64 v215, s[0:1], 0, v143, s[0:1]
	s_add_i32 s0, s2, 4
	s_min_u32 s0, s0, s57
	s_sub_i32 s0, s0, s2
	v_mad_i64_i32 v[0:1], s[0:1], s0, v179, v[0:1]
	v_add_co_u32_e64 v0, s[0:1], s78, v0
	global_load_ushort v143, v[214:215], off offset:64
	global_load_ushort v144, v[214:215], off offset:1088
	v_addc_co_u32_e64 v1, s[0:1], 0, v1, s[0:1]
	global_load_ushort v141, v[0:1], off offset:64
	global_load_ushort v142, v[0:1], off offset:1088
	global_load_dword v218, v[2:3], off
	global_load_dword v214, v[22:23], off
	global_load_dword v215, v[20:21], off
	global_load_dword v217, v[18:19], off
	v_add_co_u32_e64 v0, s[0:1], s66, v2
	s_lshl_b64 s[2:3], s[48:49], 12
	s_nop 0
	v_addc_co_u32_e64 v1, s[0:1], 0, v3, s[0:1]
	global_load_dword v219, v[0:1], off
	v_add_co_u32_e64 v0, s[0:1], s66, v22
	s_nop 1
	v_addc_co_u32_e64 v1, s[0:1], 0, v23, s[0:1]
	global_load_dword v22, v[0:1], off
	v_add_co_u32_e64 v0, s[0:1], s66, v20
	s_nop 1
	v_addc_co_u32_e64 v1, s[0:1], 0, v21, s[0:1]
	global_load_dword v23, v[0:1], off
	v_add_co_u32_e64 v0, s[0:1], s66, v18
	v_mov_b32_e32 v21, v198
	s_nop 0
	v_addc_co_u32_e64 v1, s[0:1], 0, v19, s[0:1]
	s_mul_i32 s0, s60, 0x180
	s_add_i32 s0, s0, 0
	global_load_dword v20, v[0:1], off
	v_mov_b32_e32 v18, v199
	v_mov_b32_e32 v19, s0
	s_cmp_lt_u32 s98, 4
	s_cbranch_scc1 .Lmf_skip2
	s_cmp_eq_u32 s60, 0
	s_cbranch_scc0 .Lmf_skip2
	v_and_b32_e32 v241, 15, v168
	v_bfe_u32 v242, v168, 4, 2
	v_mul_u32_u24_e32 v241, 0x180, v241
	v_mul_u32_u24_e32 v243, 0x1fc0, v242
	v_lshl_add_u32 v241, v242, 2, v241
	v_lshl_add_u32 v243, v168, 2, v243
	ds_read_b32 v244, v241
	ds_read_b32 v245, v241 offset:16
	ds_read_b32 v246, v241 offset:32
	ds_read_b32 v247, v241 offset:48
	ds_read_b32 v248, v241 offset:64
	ds_read_b32 v249, v241 offset:80
	ds_read_b32 v250, v241 offset:96
	ds_read_b32 v251, v241 offset:112
	ds_read_b32 v252, v241 offset:128
	ds_read_b32 v253, v241 offset:144
	ds_read_b32 v254, v241 offset:160
	ds_read_b32 v255, v241 offset:176
	s_waitcnt lgkmcnt(0)
	v_mfma_f32_16x16x4_f32 v[220:223], v244, v90, 0
	v_mfma_f32_16x16x4_f32 v[220:223], v245, v33, v[220:223]
	v_mfma_f32_16x16x4_f32 v[220:223], v246, v80, v[220:223]
	v_mfma_f32_16x16x4_f32 v[220:223], v247, v83, v[220:223]
	v_mfma_f32_16x16x4_f32 v[220:223], v248, v86, v[220:223]
	v_mfma_f32_16x16x4_f32 v[220:223], v249, v89, v[220:223]
	v_mfma_f32_16x16x4_f32 v[220:223], v250, v25, v[220:223]
	v_mfma_f32_16x16x4_f32 v[220:223], v251, v96, v[220:223]
	v_mfma_f32_16x16x4_f32 v[220:223], v252, v97, v[220:223]
	v_mfma_f32_16x16x4_f32 v[220:223], v253, v98, v[220:223]
	v_mfma_f32_16x16x4_f32 v[220:223], v254, v99, v[220:223]
	v_mfma_f32_16x16x4_f32 v[220:223], v255, v100, v[220:223]
	v_mfma_f32_16x16x4_f32 v[224:227], v244, v91, 0
	v_mfma_f32_16x16x4_f32 v[224:227], v245, v78, v[224:227]
	v_mfma_f32_16x16x4_f32 v[224:227], v246, v81, v[224:227]
	v_mfma_f32_16x16x4_f32 v[224:227], v247, v84, v[224:227]
	v_mfma_f32_16x16x4_f32 v[224:227], v248, v87, v[224:227]
	v_mfma_f32_16x16x4_f32 v[224:227], v249, v26, v[224:227]
	v_mfma_f32_16x16x4_f32 v[224:227], v250, v30, v[224:227]
	v_mfma_f32_16x16x4_f32 v[224:227], v251, v34, v[224:227]
	v_mfma_f32_16x16x4_f32 v[224:227], v252, v38, v[224:227]
	v_mfma_f32_16x16x4_f32 v[224:227], v253, v42, v[224:227]
	v_mfma_f32_16x16x4_f32 v[224:227], v254, v46, v[224:227]
	v_mfma_f32_16x16x4_f32 v[224:227], v255, v50, v[224:227]
	v_mfma_f32_16x16x4_f32 v[228:231], v244, v32, 0
	v_mfma_f32_16x16x4_f32 v[228:231], v245, v79, v[228:231]
	v_mfma_f32_16x16x4_f32 v[228:231], v246, v82, v[228:231]
	v_mfma_f32_16x16x4_f32 v[228:231], v247, v85, v[228:231]
	v_mfma_f32_16x16x4_f32 v[228:231], v248, v88, v[228:231]
	v_mfma_f32_16x16x4_f32 v[228:231], v249, v27, v[228:231]
	v_mfma_f32_16x16x4_f32 v[228:231], v250, v31, v[228:231]
	v_mfma_f32_16x16x4_f32 v[228:231], v251, v35, v[228:231]
	v_mfma_f32_16x16x4_f32 v[228:231], v252, v39, v[228:231]
	v_mfma_f32_16x16x4_f32 v[228:231], v253, v43, v[228:231]
	v_mfma_f32_16x16x4_f32 v[228:231], v254, v47, v[228:231]
	v_mfma_f32_16x16x4_f32 v[228:231], v255, v51, v[228:231]
	v_mfma_f32_16x16x4_f32 v[232:235], v244, v92, 0
	v_mfma_f32_16x16x4_f32 v[232:235], v245, v93, v[232:235]
	v_mfma_f32_16x16x4_f32 v[232:235], v246, v11, v[232:235]
	v_mfma_f32_16x16x4_f32 v[232:235], v247, v94, v[232:235]
	v_mfma_f32_16x16x4_f32 v[232:235], v248, v95, v[232:235]
	v_mfma_f32_16x16x4_f32 v[232:235], v249, v24, v[232:235]
	v_mfma_f32_16x16x4_f32 v[232:235], v250, v103, v[232:235]
	v_mfma_f32_16x16x4_f32 v[232:235], v251, v28, v[232:235]
	v_mfma_f32_16x16x4_f32 v[232:235], v252, v29, v[232:235]
	v_mfma_f32_16x16x4_f32 v[232:235], v253, v36, v[232:235]
	v_mfma_f32_16x16x4_f32 v[232:235], v254, v37, v[232:235]
	v_mfma_f32_16x16x4_f32 v[232:235], v255, v40, v[232:235]
	ds_read_b32 v244, v241 offset:192
	ds_read_b32 v245, v241 offset:208
	ds_read_b32 v246, v241 offset:224
	ds_read_b32 v247, v241 offset:240
	ds_read_b32 v248, v241 offset:256
	ds_read_b32 v249, v241 offset:272
	ds_read_b32 v250, v241 offset:288
	ds_read_b32 v251, v241 offset:304
	ds_read_b32 v252, v241 offset:320
	ds_read_b32 v253, v241 offset:336
	ds_read_b32 v254, v241 offset:352
	ds_read_b32 v255, v241 offset:368
	s_waitcnt lgkmcnt(0)
; __device__ __forceinline__ float bf2f(u16 v) { return __uint_as_float(((unsigned)v) << 16); }
; __device__ void phase_combine(const P& p, int l, int ntok, float* lds) {
;     ...
;         for (int m = 0; m < 96; m += 4) {
; #pragma unroll
;           for (int i = 0; i < 4; ++i) {
;             float4 s = *reinterpret_cast<const float4*>(sig + (i0 + i) * 96 + m);
;             gate[i] += s.x * g2r[m] + s.y * g2r[m + 1] + s.z * g2r[m + 2] + s.w * g2r[m + 3];
;           }
;         }
; #pragma unroll
;         for (int i = 0; i < 4; ++i) {
;           int row = r0 + i0 + i, t = tb + i0 + i;
;           float yv = bf2f((u16)y0[i]) + bf2f((u16)y1[i]);
;           float mean = wave_sum_b(yv) * (1.f / 64.f);
;           float d = yv - mean;
;           float var = wave_sum_b(d * d) * (1.f / 64.f);
;           float yn = d * rsqrtf(var + 64e-5f) * gnw + gnb;
	v_mfma_f32_16x16x4_f32 v[220:223], v244, v101, v[220:223]
	v_mfma_f32_16x16x4_f32 v[220:223], v245, v102, v[220:223]
	v_mfma_f32_16x16x4_f32 v[220:223], v246, v45, v[220:223]
	v_mfma_f32_16x16x4_f32 v[220:223], v247, v52, v[220:223]
	v_mfma_f32_16x16x4_f32 v[220:223], v248, v59, v[220:223]
	v_mfma_f32_16x16x4_f32 v[220:223], v249, v66, v[220:223]
	v_mfma_f32_16x16x4_f32 v[220:223], v250, v71, v[220:223]
	v_mfma_f32_16x16x4_f32 v[220:223], v251, v104, v[220:223]
	v_mfma_f32_16x16x4_f32 v[220:223], v252, v107, v[220:223]
	v_mfma_f32_16x16x4_f32 v[220:223], v253, v110, v[220:223]
	v_mfma_f32_16x16x4_f32 v[220:223], v254, v76, v[220:223]
	v_mfma_f32_16x16x4_f32 v[220:223], v255, v114, v[220:223]
	v_mfma_f32_16x16x4_f32 v[224:227], v244, v56, v[224:227]
	v_mfma_f32_16x16x4_f32 v[224:227], v245, v60, v[224:227]
	v_mfma_f32_16x16x4_f32 v[224:227], v246, v48, v[224:227]
	v_mfma_f32_16x16x4_f32 v[224:227], v247, v53, v[224:227]
	v_mfma_f32_16x16x4_f32 v[224:227], v248, v64, v[224:227]
	v_mfma_f32_16x16x4_f32 v[224:227], v249, v67, v[224:227]
	v_mfma_f32_16x16x4_f32 v[224:227], v250, v74, v[224:227]
	v_mfma_f32_16x16x4_f32 v[224:227], v251, v105, v[224:227]
	v_mfma_f32_16x16x4_f32 v[224:227], v252, v108, v[224:227]
	v_mfma_f32_16x16x4_f32 v[224:227], v253, v111, v[224:227]
	v_mfma_f32_16x16x4_f32 v[224:227], v254, v77, v[224:227]
	v_mfma_f32_16x16x4_f32 v[224:227], v255, v115, v[224:227]
	v_mfma_f32_16x16x4_f32 v[228:231], v244, v57, v[228:231]
	v_mfma_f32_16x16x4_f32 v[228:231], v245, v61, v[228:231]
	v_mfma_f32_16x16x4_f32 v[228:231], v246, v49, v[228:231]
	v_mfma_f32_16x16x4_f32 v[228:231], v247, v58, v[228:231]
	v_mfma_f32_16x16x4_f32 v[228:231], v248, v65, v[228:231]
	v_mfma_f32_16x16x4_f32 v[228:231], v249, v70, v[228:231]
	v_mfma_f32_16x16x4_f32 v[228:231], v250, v75, v[228:231]
	v_mfma_f32_16x16x4_f32 v[228:231], v251, v106, v[228:231]
	v_mfma_f32_16x16x4_f32 v[228:231], v252, v109, v[228:231]
	v_mfma_f32_16x16x4_f32 v[228:231], v253, v112, v[228:231]
	v_mfma_f32_16x16x4_f32 v[228:231], v254, v113, v[228:231]
	v_mfma_f32_16x16x4_f32 v[228:231], v255, v117, v[228:231]
	v_mfma_f32_16x16x4_f32 v[232:235], v244, v41, v[232:235]
	v_mfma_f32_16x16x4_f32 v[232:235], v245, v44, v[232:235]
	v_mfma_f32_16x16x4_f32 v[232:235], v246, v54, v[232:235]
	v_mfma_f32_16x16x4_f32 v[232:235], v247, v55, v[232:235]
	v_mfma_f32_16x16x4_f32 v[232:235], v248, v62, v[232:235]
	v_mfma_f32_16x16x4_f32 v[232:235], v249, v63, v[232:235]
	v_mfma_f32_16x16x4_f32 v[232:235], v250, v68, v[232:235]
	v_mfma_f32_16x16x4_f32 v[232:235], v251, v69, v[232:235]
	v_mfma_f32_16x16x4_f32 v[232:235], v252, v72, v[232:235]
	v_mfma_f32_16x16x4_f32 v[232:235], v253, v73, v[232:235]
	v_mfma_f32_16x16x4_f32 v[232:235], v254, v116, v[232:235]
	v_mfma_f32_16x16x4_f32 v[232:235], v255, v118, v[232:235]
	s_nop 7
	s_nop 3
	ds_write_b32 v243, v220 offset:8192
	ds_write_b32 v243, v221 offset:10240
	ds_write_b32 v243, v222 offset:12288
	ds_write_b32 v243, v223 offset:14336
	ds_write_b32 v243, v224 offset:8256
	ds_write_b32 v243, v225 offset:10304
	ds_write_b32 v243, v226 offset:12352
	ds_write_b32 v243, v227 offset:14400
	ds_write_b32 v243, v228 offset:8320
	ds_write_b32 v243, v229 offset:10368
	ds_write_b32 v243, v230 offset:12416
	ds_write_b32 v243, v231 offset:14464
	ds_write_b32 v243, v232 offset:8384
	ds_write_b32 v243, v233 offset:10432
	ds_write_b32 v243, v234 offset:12480
	ds_write_b32 v243, v235 offset:14528
	s_waitcnt lgkmcnt(0)
.Lmf_skip2:
	v_lshlrev_b32_e32 v244, 2, v168
	v_lshl_add_u32 v244, s60, 11, v244
	ds_read_b32 v221, v244 offset:8192
	ds_read_b32 v222, v244 offset:10240
	ds_read_b32 v223, v244 offset:12288
	ds_read_b32 v0, v244 offset:14336
	s_waitcnt vmcnt(30)
	s_waitcnt vmcnt(29)
	s_waitcnt vmcnt(4)
	s_waitcnt vmcnt(0)
	s_waitcnt lgkmcnt(0)
	v_lshlrev_b32_e32 v197, 16, v197
	v_lshlrev_b32_e32 v192, 16, v192
	v_lshlrev_b32_e32 v164, 16, v164
	v_lshlrev_b32_e32 v158, 16, v158
	v_lshlrev_b32_e32 v152, 16, v152
	v_lshlrev_b32_e32 v138, 16, v138
	v_lshlrev_b32_e32 v1, 16, v201
	v_lshlrev_b32_e32 v2, 16, v202
	v_add_f32_e32 v1, v2, v1
	v_mov_b32_e32 v3, v129
	s_nop 0
	v_add_f32_dpp v2, v1, v1 quad_perm:[1,0,3,2] row_mask:0xf bank_mask:0xf bound_ctrl:1
	s_nop 1
	v_add_f32_dpp v2, v2, v2 quad_perm:[2,3,0,1] row_mask:0xf bank_mask:0xf bound_ctrl:1
	s_nop 1
	v_add_f32_dpp v2, v2, v2 row_half_mirror row_mask:0xf bank_mask:0xf bound_ctrl:1
	s_nop 1
	v_add_f32_dpp v2, v2, v2 row_mirror row_mask:0xf bank_mask:0xf bound_ctrl:1
	s_nop 1
	v_mov_b32_dpp v3, v2 row_bcast:15 row_mask:0xa bank_mask:0xf
	v_add_f32_e32 v2, v2, v3
	v_mov_b32_e32 v3, v129
	s_nop 1
	v_mov_b32_dpp v3, v2 row_bcast:31 row_mask:0xc bank_mask:0xf
	v_add_f32_e32 v2, v2, v3
	v_mov_b32_e32 v3, v129
	v_readlane_b32 s0, v2, 63
	s_nop 1
	v_fmac_f32_e32 v1, s0, v180
	v_mul_f32_e32 v2, v1, v1
	s_nop 1
	v_mov_b32_dpp v2, v2 quad_perm:[1,0,3,2] row_mask:0xf bank_mask:0xf bound_ctrl:1
	v_fmac_f32_e32 v2, v1, v1
	s_nop 1
	v_add_f32_dpp v2, v2, v2 quad_perm:[2,3,0,1] row_mask:0xf bank_mask:0xf bound_ctrl:1
	s_nop 1
	v_add_f32_dpp v2, v2, v2 row_half_mirror row_mask:0xf bank_mask:0xf bound_ctrl:1
	s_nop 1
	v_add_f32_dpp v2, v2, v2 row_mirror row_mask:0xf bank_mask:0xf bound_ctrl:1
	s_nop 1
	v_mov_b32_dpp v3, v2 row_bcast:15 row_mask:0xa bank_mask:0xf
	v_add_f32_e32 v2, v2, v3
	v_mov_b32_e32 v3, v129
	s_nop 1
	v_mov_b32_dpp v3, v2 row_bcast:31 row_mask:0xc bank_mask:0xf
	v_add_f32_e32 v2, v2, v3
	s_nop 0
	v_readlane_b32 s0, v2, 63
	s_nop 1
	v_fma_f32 v2, s0, v181, v170
	v_cmp_gt_f32_e64 s[0:1], s33, v2
	v_mul_f32_e32 v3, 0x4b800000, v2
	s_nop 0
	v_cndmask_b32_e64 v2, v2, v3, s[0:1]
	v_rsq_f32_e32 v2, v2
	s_nop 0
	v_mul_f32_e32 v3, 0x45800000, v2
; __device__ __forceinline__ float bf2f(u16 v) { return __uint_as_float(((unsigned)v) << 16); }
; __device__ void phase_combine(const P& p, int l, int ntok, float* lds) {
;     ...
;         for (int i = 0; i < 4; ++i) {
;           int row = r0 + i0 + i, t = tb + i0 + i;
;           float yv = bf2f((u16)y0[i]) + bf2f((u16)y1[i]);
;           float mean = wave_sum_b(yv) * (1.f / 64.f);
;           float d = yv - mean;
;           float var = wave_sum_b(d * d) * (1.f / 64.f);
;           float yn = d * rsqrtf(var + 64e-5f) * gnw + gnb;
;           float v_c = bf2f((u16)vc[i]), v_p = t > 0 ? bf2f((u16)vp[i]) : 0.f, v_n = t < T - 1 ? bf2f((u16)vn[i]) : 0.f;
;           float vf = v_c + (v_p - v_c) * muvf, vb = v_c + (v_n - v_c) * muvb;
;           float bonus = sf[i] * vf + sb[i] * vb;
;           p.nbuf[(size_t)row * D + 1536 + tid] = f2bf((yn + bonus) * gate[i]);
;         }
	v_cndmask_b32_e64 v2, v2, v3, s[0:1]
	v_mul_f32_e32 v1, v1, v2
	v_lshlrev_b32_e32 v2, 16, v18
	v_lshlrev_b32_e32 v3, 16, v208
	v_lshlrev_b32_e32 v18, 16, v210
	v_cndmask_b32_e64 v3, v3, 0, s[52:53]
	v_cndmask_b32_e64 v18, 0, v18, s[44:45]
	v_sub_f32_e32 v3, v3, v2
	v_sub_f32_e32 v18, v18, v2
	v_fma_f32 v3, v121, v3, v2
	v_fmac_f32_e32 v2, v122, v18
	v_mul_f32_e32 v2, v219, v2
	v_fma_f32 v1, v119, v1, v120
	v_fmac_f32_e32 v2, v218, v3
	v_add_f32_e32 v1, v2, v1
	v_mul_f32_e32 v1, v221, v1
	v_bfe_u32 v2, v1, 16, 1
	s_lshl_b64 s[44:45], s[46:47], 12
	v_add3_u32 v1, v1, v2, s21
	v_lshl_add_u64 v[18:19], v[14:15], 0, s[44:45]
	global_store_short_d16_hi v[18:19], v1, off offset:3072
	v_lshlrev_b32_e32 v1, 16, v212
	v_lshlrev_b32_e32 v2, 16, v213
	v_add_f32_e32 v1, v2, v1
	v_mov_b32_e32 v3, v129
	s_nop 0
	v_add_f32_dpp v2, v1, v1 quad_perm:[1,0,3,2] row_mask:0xf bank_mask:0xf bound_ctrl:1
	s_nop 1
	v_add_f32_dpp v2, v2, v2 quad_perm:[2,3,0,1] row_mask:0xf bank_mask:0xf bound_ctrl:1
	s_nop 1
	v_add_f32_dpp v2, v2, v2 row_half_mirror row_mask:0xf bank_mask:0xf bound_ctrl:1
	s_nop 1
	v_add_f32_dpp v2, v2, v2 row_mirror row_mask:0xf bank_mask:0xf bound_ctrl:1
	s_nop 1
	v_mov_b32_dpp v3, v2 row_bcast:15 row_mask:0xa bank_mask:0xf
	v_add_f32_e32 v2, v2, v3
	v_mov_b32_e32 v3, v129
	s_nop 1
	v_mov_b32_dpp v3, v2 row_bcast:31 row_mask:0xc bank_mask:0xf
	v_add_f32_e32 v2, v2, v3
	v_mov_b32_e32 v3, v129
	v_readlane_b32 s0, v2, 63
	s_nop 1
	v_fmac_f32_e32 v1, s0, v180
	v_mul_f32_e32 v2, v1, v1
	s_nop 1
	v_mov_b32_dpp v2, v2 quad_perm:[1,0,3,2] row_mask:0xf bank_mask:0xf bound_ctrl:1
	v_fmac_f32_e32 v2, v1, v1
	s_nop 1
	v_add_f32_dpp v2, v2, v2 quad_perm:[2,3,0,1] row_mask:0xf bank_mask:0xf bound_ctrl:1
	s_nop 1
	v_add_f32_dpp v2, v2, v2 row_half_mirror row_mask:0xf bank_mask:0xf bound_ctrl:1
	s_nop 1
	v_add_f32_dpp v2, v2, v2 row_mirror row_mask:0xf bank_mask:0xf bound_ctrl:1
	s_nop 1
	v_mov_b32_dpp v3, v2 row_bcast:15 row_mask:0xa bank_mask:0xf
	v_add_f32_e32 v2, v2, v3
	v_mov_b32_e32 v3, v129
	s_nop 1
	v_mov_b32_dpp v3, v2 row_bcast:31 row_mask:0xc bank_mask:0xf
	v_add_f32_e32 v2, v2, v3
	s_nop 0
	v_readlane_b32 s0, v2, 63
	s_nop 1
	v_fma_f32 v2, s0, v181, v170
	v_cmp_gt_f32_e64 s[0:1], s33, v2
	v_mul_f32_e32 v3, 0x4b800000, v2
	s_nop 0
	v_cndmask_b32_e64 v2, v2, v3, s[0:1]
	v_rsq_f32_e32 v2, v2
	s_nop 0
	v_mul_f32_e32 v3, 0x45800000, v2
	v_cndmask_b32_e64 v2, v2, v3, s[0:1]
	v_mul_f32_e32 v1, v1, v2
	v_lshlrev_b32_e32 v2, 16, v21
	v_lshlrev_b32_e32 v21, 16, v206
	v_lshlrev_b32_e32 v3, 16, v199
	v_cndmask_b32_e64 v21, 0, v21, s[42:43]
	v_sub_f32_e32 v3, v3, v2
	v_sub_f32_e32 v21, v21, v2
	v_fma_f32 v3, v121, v3, v2
	v_fmac_f32_e32 v2, v122, v21
	v_mul_f32_e32 v2, v20, v2
	v_fma_f32 v1, v119, v1, v120
	v_fmac_f32_e32 v2, v217, v3
	v_add_f32_e32 v1, v2, v1
	v_mul_f32_e32 v1, v222, v1
	v_bfe_u32 v2, v1, 16, 1
	s_lshl_b64 s[42:43], s[50:51], 12
	v_add3_u32 v1, v1, v2, s21
	v_lshl_add_u64 v[20:21], v[14:15], 0, s[42:43]
	global_store_short_d16_hi v[20:21], v1, off offset:3072
	v_lshlrev_b32_e32 v1, 16, v209
	v_lshlrev_b32_e32 v2, 16, v211
	v_add_f32_e32 v1, v2, v1
	v_mov_b32_e32 v3, v129
	s_nop 0
	v_add_f32_dpp v2, v1, v1 quad_perm:[1,0,3,2] row_mask:0xf bank_mask:0xf bound_ctrl:1
	s_nop 1
	v_add_f32_dpp v2, v2, v2 quad_perm:[2,3,0,1] row_mask:0xf bank_mask:0xf bound_ctrl:1
	s_nop 1
	v_add_f32_dpp v2, v2, v2 row_half_mirror row_mask:0xf bank_mask:0xf bound_ctrl:1
	s_nop 1
	v_add_f32_dpp v2, v2, v2 row_mirror row_mask:0xf bank_mask:0xf bound_ctrl:1
	s_nop 1
	v_mov_b32_dpp v3, v2 row_bcast:15 row_mask:0xa bank_mask:0xf
	v_add_f32_e32 v2, v2, v3
	v_mov_b32_e32 v3, v129
	s_nop 1
	v_mov_b32_dpp v3, v2 row_bcast:31 row_mask:0xc bank_mask:0xf
	v_add_f32_e32 v2, v2, v3
	v_mov_b32_e32 v3, v129
	v_readlane_b32 s0, v2, 63
	s_nop 1
	v_fmac_f32_e32 v1, s0, v180
	v_mul_f32_e32 v2, v1, v1
	s_nop 1
	v_mov_b32_dpp v2, v2 quad_perm:[1,0,3,2] row_mask:0xf bank_mask:0xf bound_ctrl:1
	v_fmac_f32_e32 v2, v1, v1
	s_nop 1
	v_add_f32_dpp v2, v2, v2 quad_perm:[2,3,0,1] row_mask:0xf bank_mask:0xf bound_ctrl:1
	s_nop 1
	v_add_f32_dpp v2, v2, v2 row_half_mirror row_mask:0xf bank_mask:0xf bound_ctrl:1
	s_nop 1
	v_add_f32_dpp v2, v2, v2 row_mirror row_mask:0xf bank_mask:0xf bound_ctrl:1
	s_nop 1
	v_mov_b32_dpp v3, v2 row_bcast:15 row_mask:0xa bank_mask:0xf
	v_add_f32_e32 v2, v2, v3
	v_mov_b32_e32 v3, v129
	s_nop 1
	v_mov_b32_dpp v3, v2 row_bcast:31 row_mask:0xc bank_mask:0xf
	v_add_f32_e32 v2, v2, v3
	s_nop 0
	v_readlane_b32 s0, v2, 63
	s_nop 1
	v_fma_f32 v2, s0, v181, v170
	v_cmp_gt_f32_e64 s[0:1], s33, v2
	v_mul_f32_e32 v3, 0x4b800000, v2
	s_nop 0
	v_cndmask_b32_e64 v2, v2, v3, s[0:1]
	v_rsq_f32_e32 v2, v2
	s_nop 0
	v_mul_f32_e32 v3, 0x45800000, v2
	v_cndmask_b32_e64 v2, v2, v3, s[0:1]
	v_lshlrev_b32_e32 v3, 16, v198
	v_lshlrev_b32_e32 v198, 16, v204
	v_mul_f32_e32 v1, v1, v2
	v_lshlrev_b32_e32 v2, 16, v216
	v_cndmask_b32_e64 v198, 0, v198, s[40:41]
	v_sub_f32_e32 v3, v3, v2
	v_sub_f32_e32 v198, v198, v2
	v_fma_f32 v3, v121, v3, v2
	v_fmac_f32_e32 v2, v122, v198
	v_mul_f32_e32 v2, v23, v2
	v_fma_f32 v1, v119, v1, v120
	v_fmac_f32_e32 v2, v215, v3
	v_add_f32_e32 v1, v2, v1
	v_mul_f32_e32 v1, v223, v1
	v_bfe_u32 v2, v1, 16, 1
	v_add3_u32 v1, v1, v2, s21
	v_lshl_add_u64 v[2:3], v[14:15], 0, s[2:3]
	global_store_short_d16_hi v[2:3], v1, off offset:3072
	v_lshlrev_b32_e32 v1, 16, v205
	v_lshlrev_b32_e32 v23, 16, v207
	v_add_f32_e32 v1, v23, v1
	v_mov_b32_e32 v198, v129
	s_nop 0
	v_add_f32_dpp v23, v1, v1 quad_perm:[1,0,3,2] row_mask:0xf bank_mask:0xf bound_ctrl:1
	s_nop 1
	v_add_f32_dpp v23, v23, v23 quad_perm:[2,3,0,1] row_mask:0xf bank_mask:0xf bound_ctrl:1
	s_nop 1
; __device__ __forceinline__ float bf2f(u16 v) { return __uint_as_float(((unsigned)v) << 16); }
; __device__ __forceinline__ float siluf_(float x) { return x / (1.f + __expf(-x)); }
; __device__ void phase_combine(const P& p, int l, int ntok, float* lds) {
;     ...
;         for (int i = 0; i < 4; ++i) {
;           int row = r0 + i0 + i, t = tb + i0 + i;
;           float yv = bf2f((u16)y0[i]) + bf2f((u16)y1[i]);
;           float mean = wave_sum_b(yv) * (1.f / 64.f);
;           float d = yv - mean;
;           float var = wave_sum_b(d * d) * (1.f / 64.f);
;           float yn = d * rsqrtf(var + 64e-5f) * gnw + gnb;
;           float v_c = bf2f((u16)vc[i]), v_p = t > 0 ? bf2f((u16)vp[i]) : 0.f, v_n = t < T - 1 ? bf2f((u16)vn[i]) : 0.f;
;           float vf = v_c + (v_p - v_c) * muvf, vb = v_c + (v_n - v_c) * muvb;
;           float bonus = sf[i] * vf + sb[i] * vb;
;           p.nbuf[(size_t)row * D + 1536 + tid] = f2bf((yn + bonus) * gate[i]);
;         }
;       }
; #pragma unroll
;       for (int i = 0; i < 4; ++i) {
;         int row = r0 + i0 + i;
;         float o0 = bf2f((u16)a0[i]) + bf2f((u16)a1[i]), o1 = bf2f((u16)a2[i]) + bf2f((u16)a3[i]);
;         float ss = wave_sum_b(o0 * o0 + o1 * o1);
;         float rstd = rsqrtf(ss * (1.f / 128.f) + 1e-6f);
;         u16* dst = p.nbuf + (size_t)row * D + mixer * 512 + hh * 128 + lane;
;         dst[0] = f2bf(o0 * rstd * ng0 * siluf_(bf2f((u16)g0r[i])));
;         dst[64] = f2bf(o1 * rstd * ng1 * siluf_(bf2f((u16)g1r[i])));
	v_add_f32_dpp v23, v23, v23 row_half_mirror row_mask:0xf bank_mask:0xf bound_ctrl:1
	s_nop 1
	v_add_f32_dpp v23, v23, v23 row_mirror row_mask:0xf bank_mask:0xf bound_ctrl:1
	s_nop 1
	v_mov_b32_dpp v198, v23 row_bcast:15 row_mask:0xa bank_mask:0xf
	v_add_f32_e32 v23, v23, v198
	v_mov_b32_e32 v198, v129
	s_nop 1
	v_mov_b32_dpp v198, v23 row_bcast:31 row_mask:0xc bank_mask:0xf
	v_add_f32_e32 v23, v23, v198
	v_mov_b32_e32 v198, v129
	v_readlane_b32 s0, v23, 63
	s_nop 1
	v_fmac_f32_e32 v1, s0, v180
	v_mul_f32_e32 v23, v1, v1
	s_nop 1
	v_mov_b32_dpp v23, v23 quad_perm:[1,0,3,2] row_mask:0xf bank_mask:0xf bound_ctrl:1
	v_fmac_f32_e32 v23, v1, v1
	s_nop 1
	v_add_f32_dpp v23, v23, v23 quad_perm:[2,3,0,1] row_mask:0xf bank_mask:0xf bound_ctrl:1
	s_nop 1
	v_add_f32_dpp v23, v23, v23 row_half_mirror row_mask:0xf bank_mask:0xf bound_ctrl:1
	s_nop 1
	v_add_f32_dpp v23, v23, v23 row_mirror row_mask:0xf bank_mask:0xf bound_ctrl:1
	s_nop 1
	v_mov_b32_dpp v198, v23 row_bcast:15 row_mask:0xa bank_mask:0xf
	v_add_f32_e32 v23, v23, v198
	v_mov_b32_e32 v198, v129
	s_nop 1
	v_mov_b32_dpp v198, v23 row_bcast:31 row_mask:0xc bank_mask:0xf
	v_add_f32_e32 v23, v23, v198
	s_nop 0
	v_readlane_b32 s0, v23, 63
	s_nop 1
	v_fma_f32 v23, s0, v181, v170
	v_cmp_gt_f32_e64 s[0:1], s33, v23
	v_mul_f32_e32 v198, 0x4b800000, v23
	s_nop 0
	v_cndmask_b32_e64 v23, v23, v198, s[0:1]
	v_rsq_f32_e32 v23, v23
	s_nop 0
	v_mul_f32_e32 v198, 0x45800000, v23
	v_cndmask_b32_e64 v23, v23, v198, s[0:1]
	v_lshlrev_b32_e32 v198, 16, v203
	v_mul_f32_e32 v1, v1, v23
	v_lshlrev_b32_e32 v23, 16, v200
	v_cndmask_b32_e32 v198, 0, v198, vcc
	v_sub_f32_e32 v197, v197, v23
	v_sub_f32_e32 v198, v198, v23
	v_fma_f32 v197, v121, v197, v23
	v_fmac_f32_e32 v23, v122, v198
	v_mul_f32_e32 v22, v22, v23
	v_fma_f32 v1, v119, v1, v120
	v_fmac_f32_e32 v22, v214, v197
	v_add_f32_e32 v1, v22, v1
	v_mul_f32_e32 v0, v0, v1
	v_bfe_u32 v1, v0, 16, 1
	s_lshl_b64 s[0:1], s[36:37], 12
	v_add3_u32 v22, v0, v1, s21
	v_lshl_add_u64 v[0:1], v[14:15], 0, s[0:1]
	global_store_short_d16_hi v[0:1], v22, off offset:3072
	v_lshlrev_b32_e32 v22, 16, v195
	v_lshlrev_b32_e32 v23, 16, v196
	v_lshlrev_b32_e32 v196, 16, v193
	v_lshlrev_b32_e32 v197, 16, v194
	v_pk_add_f32 v[22:23], v[22:23], v[196:197]
	v_mul_f32_e32 v196, 0xbfb8aa3b, v192
	v_pk_mul_f32 v[194:195], v[22:23], v[22:23]
	v_exp_f32_e32 v196, v196
	v_add_f32_e32 v193, v194, v195
	v_mov_b32_e32 v194, v129
	v_add_f32_e32 v196, 1.0, v196
	v_add_f32_dpp v193, v193, v193 quad_perm:[1,0,3,2] row_mask:0xf bank_mask:0xf bound_ctrl:1
	s_nop 0
	s_nop 0
	v_add_f32_dpp v193, v193, v193 quad_perm:[2,3,0,1] row_mask:0xf bank_mask:0xf bound_ctrl:1
	s_nop 0
	s_nop 0
	v_add_f32_dpp v193, v193, v193 row_half_mirror row_mask:0xf bank_mask:0xf bound_ctrl:1
	s_nop 0
	s_nop 0
	v_add_f32_dpp v193, v193, v193 row_mirror row_mask:0xf bank_mask:0xf bound_ctrl:1
	s_nop 0
	s_nop 0
	v_mov_b32_dpp v194, v193 row_bcast:15 row_mask:0xa bank_mask:0xf
	v_add_f32_e32 v193, v193, v194
	v_mov_b32_e32 v194, v129
	s_nop 1
	v_mov_b32_dpp v194, v193 row_bcast:31 row_mask:0xc bank_mask:0xf
	v_add_f32_e32 v193, v193, v194
	s_nop 0
	v_readlane_b32 s20, v193, 63
	s_nop 1
	v_fma_f32 v193, s20, v182, v169
	v_cmp_gt_f32_e32 vcc, s33, v193
	v_mul_f32_e32 v194, 0x4b800000, v193
	s_nop 0
	v_cndmask_b32_e32 v193, v193, v194, vcc
	v_rsq_f32_e32 v193, v193
	s_nop 0
	v_mul_f32_e32 v194, 0x45800000, v193
	v_cndmask_b32_e32 v193, v193, v194, vcc
	v_mul_f32_e32 v22, v22, v193
	v_mul_f32_e32 v22, v126, v22
	v_rcp_f32_e32 v197, v196
	s_nop 0
	v_mul_f32_e32 v192, v192, v197
	v_mul_f32_e32 v22, v192, v22
	v_bfe_u32 v192, v22, 16, 1
	v_lshl_add_u64 v[194:195], v[12:13], 0, s[44:45]
	v_add3_u32 v22, v22, v192, s21
	global_store_short_d16_hi v[194:195], v22, off
	v_mul_f32_e32 v22, v23, v193
	v_lshlrev_b32_e32 v23, 16, v191
	v_mul_f32_e32 v191, 0xbfb8aa3b, v23
	v_exp_f32_e32 v191, v191
	v_mul_f32_e32 v22, v127, v22
	v_add_f32_e32 v191, 1.0, v191
	s_nop 0
	v_rcp_f32_e32 v192, v191
	s_nop 0
	v_mul_f32_e32 v23, v23, v192
	v_mul_f32_e32 v22, v23, v22
	v_bfe_u32 v23, v22, 16, 1
	v_add3_u32 v22, v22, v23, s21
	global_store_short_d16_hi v[194:195], v22, off offset:128
	v_lshlrev_b32_e32 v22, 16, v167
	v_lshlrev_b32_e32 v23, 16, v190
	v_lshlrev_b32_e32 v190, 16, v165
	v_lshlrev_b32_e32 v191, 16, v166
	v_pk_add_f32 v[22:23], v[22:23], v[190:191]
	v_mul_f32_e32 v190, 0xbfb8aa3b, v164
	v_pk_mul_f32 v[166:167], v[22:23], v[22:23]
	v_exp_f32_e32 v190, v190
	v_add_f32_e32 v165, v166, v167
	v_mov_b32_e32 v166, v129
	v_add_f32_e32 v190, 1.0, v190
	v_add_f32_dpp v165, v165, v165 quad_perm:[1,0,3,2] row_mask:0xf bank_mask:0xf bound_ctrl:1
	s_nop 0
	s_nop 0
	v_add_f32_dpp v165, v165, v165 quad_perm:[2,3,0,1] row_mask:0xf bank_mask:0xf bound_ctrl:1
	s_nop 0
	s_nop 0
	v_add_f32_dpp v165, v165, v165 row_half_mirror row_mask:0xf bank_mask:0xf bound_ctrl:1
	s_nop 0
	s_nop 0
	v_add_f32_dpp v165, v165, v165 row_mirror row_mask:0xf bank_mask:0xf bound_ctrl:1
	s_nop 0
	s_nop 0
	v_mov_b32_dpp v166, v165 row_bcast:15 row_mask:0xa bank_mask:0xf
	v_add_f32_e32 v165, v165, v166
	v_mov_b32_e32 v166, v129
	s_nop 1
	v_mov_b32_dpp v166, v165 row_bcast:31 row_mask:0xc bank_mask:0xf
	v_add_f32_e32 v165, v165, v166
	s_nop 0
	v_readlane_b32 s20, v165, 63
	s_nop 1
	v_fma_f32 v165, s20, v182, v169
	v_cmp_gt_f32_e32 vcc, s33, v165
	v_mul_f32_e32 v166, 0x4b800000, v165
	s_nop 0
	v_cndmask_b32_e32 v165, v165, v166, vcc
	v_rsq_f32_e32 v165, v165
	s_nop 0
	v_mul_f32_e32 v166, 0x45800000, v165
	v_cndmask_b32_e32 v165, v165, v166, vcc
	v_mul_f32_e32 v22, v22, v165
	v_mul_f32_e32 v22, v126, v22
	v_rcp_f32_e32 v191, v190
	s_nop 0
	v_mul_f32_e32 v164, v164, v191
	v_mul_f32_e32 v22, v164, v22
; __device__ __forceinline__ float bf2f(u16 v) { return __uint_as_float(((unsigned)v) << 16); }
; __device__ __forceinline__ float siluf_(float x) { return x / (1.f + __expf(-x)); }
; __device__ void phase_combine(const P& p, int l, int ntok, float* lds) {
;     ...
;       for (int i = 0; i < 4; ++i) {
;         int row = r0 + i0 + i;
;         float o0 = bf2f((u16)a0[i]) + bf2f((u16)a1[i]), o1 = bf2f((u16)a2[i]) + bf2f((u16)a3[i]);
;         float ss = wave_sum_b(o0 * o0 + o1 * o1);
;         float rstd = rsqrtf(ss * (1.f / 128.f) + 1e-6f);
;         u16* dst = p.nbuf + (size_t)row * D + mixer * 512 + hh * 128 + lane;
;         dst[0] = f2bf(o0 * rstd * ng0 * siluf_(bf2f((u16)g0r[i])));
;         dst[64] = f2bf(o1 * rstd * ng1 * siluf_(bf2f((u16)g1r[i])));
;       }
; #pragma unroll
;       for (int i = 0; i < 4; ++i) {
;         int tr = (tb + i0 + i) & (RL - 1);
;         float up = tr != 0 ? bf2f((u16)ucc[i]) * bf2f((u16)uch[i]) : 0.f;
;         float uc = bf2f((u16)ucc[i + 1]) * bf2f((u16)uch[i + 1]);
;         float un = tr != RL - 1 ? bf2f((u16)ucc[i + 2]) * bf2f((u16)uch[i + 2]) : 0.f;
;         float cv = scw0 * up + scw1 * uc + scw2 * un;
;         p.nbuf[(size_t)(r0 + i0 + i) * D + 1024 + tid] = f2bf(bf2f((u16)cbr[i]) * cv);
;       }
	v_bfe_u32 v164, v22, 16, 1
	v_lshl_add_u64 v[166:167], v[12:13], 0, s[42:43]
	v_add3_u32 v22, v22, v164, s21
	global_store_short_d16_hi v[166:167], v22, off
	v_mul_f32_e32 v22, v23, v165
	v_lshlrev_b32_e32 v23, 16, v163
	v_mul_f32_e32 v163, 0xbfb8aa3b, v23
	v_exp_f32_e32 v163, v163
	v_mul_f32_e32 v22, v127, v22
	v_add_f32_e32 v163, 1.0, v163
	s_nop 0
	v_rcp_f32_e32 v164, v163
	s_nop 0
	v_mul_f32_e32 v23, v23, v164
	v_mul_f32_e32 v22, v23, v22
	v_bfe_u32 v23, v22, 16, 1
	v_add3_u32 v22, v22, v23, s21
	global_store_short_d16_hi v[166:167], v22, off offset:128
	v_lshlrev_b32_e32 v22, 16, v161
	v_lshlrev_b32_e32 v23, 16, v162
	v_lshlrev_b32_e32 v162, 16, v159
	v_lshlrev_b32_e32 v163, 16, v160
	v_pk_add_f32 v[22:23], v[22:23], v[162:163]
	v_mul_f32_e32 v162, 0xbfb8aa3b, v158
	v_pk_mul_f32 v[160:161], v[22:23], v[22:23]
	v_exp_f32_e32 v162, v162
	v_add_f32_e32 v159, v160, v161
	v_mov_b32_e32 v160, v129
	v_add_f32_e32 v162, 1.0, v162
	v_add_f32_dpp v159, v159, v159 quad_perm:[1,0,3,2] row_mask:0xf bank_mask:0xf bound_ctrl:1
	s_nop 1
	v_add_f32_dpp v159, v159, v159 quad_perm:[2,3,0,1] row_mask:0xf bank_mask:0xf bound_ctrl:1
	s_nop 1
	v_add_f32_dpp v159, v159, v159 row_half_mirror row_mask:0xf bank_mask:0xf bound_ctrl:1
	s_nop 1
	v_add_f32_dpp v159, v159, v159 row_mirror row_mask:0xf bank_mask:0xf bound_ctrl:1
	s_nop 1
	v_mov_b32_dpp v160, v159 row_bcast:15 row_mask:0xa bank_mask:0xf
	v_add_f32_e32 v159, v159, v160
	v_mov_b32_e32 v160, v129
	s_nop 1
	v_mov_b32_dpp v160, v159 row_bcast:31 row_mask:0xc bank_mask:0xf
	v_add_f32_e32 v159, v159, v160
	s_nop 0
	v_readlane_b32 s20, v159, 63
	s_nop 1
	v_fma_f32 v159, s20, v182, v169
	v_cmp_gt_f32_e32 vcc, s33, v159
	v_mul_f32_e32 v160, 0x4b800000, v159
	s_nop 0
	v_cndmask_b32_e32 v159, v159, v160, vcc
	v_rsq_f32_e32 v159, v159
	s_nop 0
	v_mul_f32_e32 v160, 0x45800000, v159
	v_cndmask_b32_e32 v159, v159, v160, vcc
	v_lshl_add_u64 v[160:161], v[12:13], 0, s[2:3]
	v_mul_f32_e32 v22, v22, v159
	v_mul_f32_e32 v22, v126, v22
	v_rcp_f32_e32 v163, v162
	s_nop 0
	v_mul_f32_e32 v158, v158, v163
	v_mul_f32_e32 v22, v158, v22
	v_bfe_u32 v158, v22, 16, 1
	v_add3_u32 v22, v22, v158, s21
	global_store_short_d16_hi v[160:161], v22, off
	v_mul_f32_e32 v22, v23, v159
	v_lshlrev_b32_e32 v23, 16, v157
	v_mul_f32_e32 v157, 0xbfb8aa3b, v23
	v_exp_f32_e32 v157, v157
	v_mul_f32_e32 v22, v127, v22
	v_add_f32_e32 v157, 1.0, v157
	s_nop 0
	v_rcp_f32_e32 v158, v157
	s_nop 0
	v_mul_f32_e32 v23, v23, v158
	v_mul_f32_e32 v22, v23, v22
	v_bfe_u32 v23, v22, 16, 1
	v_add3_u32 v22, v22, v23, s21
	global_store_short_d16_hi v[160:161], v22, off offset:128
	v_lshlrev_b32_e32 v22, 16, v155
	v_lshlrev_b32_e32 v23, 16, v156
	v_lshlrev_b32_e32 v156, 16, v153
	v_lshlrev_b32_e32 v157, 16, v154
	v_pk_add_f32 v[22:23], v[22:23], v[156:157]
	v_mul_f32_e32 v156, 0xbfb8aa3b, v152
	v_pk_mul_f32 v[154:155], v[22:23], v[22:23]
	v_exp_f32_e32 v156, v156
	v_add_f32_e32 v153, v154, v155
	v_mov_b32_e32 v154, v129
	v_add_f32_e32 v156, 1.0, v156
	v_add_f32_dpp v153, v153, v153 quad_perm:[1,0,3,2] row_mask:0xf bank_mask:0xf bound_ctrl:1
	s_nop 1
	v_add_f32_dpp v153, v153, v153 quad_perm:[2,3,0,1] row_mask:0xf bank_mask:0xf bound_ctrl:1
	s_nop 1
	v_add_f32_dpp v153, v153, v153 row_half_mirror row_mask:0xf bank_mask:0xf bound_ctrl:1
	s_nop 1
	v_add_f32_dpp v153, v153, v153 row_mirror row_mask:0xf bank_mask:0xf bound_ctrl:1
	s_nop 1
	v_mov_b32_dpp v154, v153 row_bcast:15 row_mask:0xa bank_mask:0xf
	v_add_f32_e32 v153, v153, v154
	v_mov_b32_e32 v154, v129
	s_nop 1
	v_mov_b32_dpp v154, v153 row_bcast:31 row_mask:0xc bank_mask:0xf
	v_add_f32_e32 v153, v153, v154
	s_nop 0
	v_readlane_b32 s2, v153, 63
	s_nop 1
	v_fma_f32 v153, s2, v182, v169
	v_cmp_gt_f32_e32 vcc, s33, v153
	v_mul_f32_e32 v154, 0x4b800000, v153
	s_nop 0
	v_cndmask_b32_e32 v153, v153, v154, vcc
	v_rsq_f32_e32 v153, v153
	s_nop 0
	v_mul_f32_e32 v154, 0x45800000, v153
	v_cndmask_b32_e32 v153, v153, v154, vcc
	v_lshl_add_u64 v[154:155], v[12:13], 0, s[0:1]
	v_mul_f32_e32 v22, v22, v153
	v_mul_f32_e32 v22, v126, v22
	v_rcp_f32_e32 v157, v156
	s_nop 0
	v_mul_f32_e32 v152, v152, v157
	v_mul_f32_e32 v22, v152, v22
	v_bfe_u32 v152, v22, 16, 1
	v_add3_u32 v22, v22, v152, s21
	global_store_short_d16_hi v[154:155], v22, off
	v_mul_f32_e32 v22, v23, v153
	v_lshlrev_b32_e32 v23, 16, v149
	v_mul_f32_e32 v149, 0xbfb8aa3b, v23
	v_exp_f32_e32 v149, v149
	v_mul_f32_e32 v22, v127, v22
	v_add_f32_e32 v149, 1.0, v149
	s_and_b32 s0, s46, s58
	s_cmp_lg_u32 s0, 0
	v_rcp_f32_e32 v152, v149
	s_nop 0
	v_mul_f32_e32 v23, v23, v152
	v_mul_f32_e32 v22, v23, v22
	v_bfe_u32 v23, v22, 16, 1
	v_add3_u32 v22, v22, v23, s21
	global_store_short_d16_hi v[154:155], v22, off offset:128
	v_lshlrev_b32_e32 v22, 16, v139
	v_lshlrev_b32_e32 v23, 16, v140
	v_mul_f32_e32 v22, v22, v23
	s_cselect_b64 vcc, -1, 0
	v_cndmask_b32_e32 v22, 0, v22, vcc
	v_lshlrev_b32_e32 v23, 16, v147
	v_lshlrev_b32_e32 v139, 16, v148
	v_mul_f32_e32 v23, v23, v139
	v_lshlrev_b32_e32 v139, 16, v150
	v_lshlrev_b32_e32 v140, 16, v151
	v_mul_f32_e32 v22, v123, v22
	v_mul_f32_e32 v139, v139, v140
	v_fmac_f32_e32 v22, v124, v23
	v_fmac_f32_e32 v22, v125, v139
	v_mul_f32_e32 v22, v22, v138
	v_bfe_u32 v138, v22, 16, 1
	v_add3_u32 v22, v22, v138, s21
	global_store_short_d16_hi v[18:19], v22, off offset:2048
	v_lshlrev_b32_e32 v18, 16, v145
	v_lshlrev_b32_e32 v19, 16, v146
	v_mul_f32_e32 v18, v18, v19
	v_mul_f32_e32 v19, v124, v139
	v_fmac_f32_e32 v19, v123, v23
	v_fmac_f32_e32 v19, v125, v18
	v_lshlrev_b32_e32 v22, 16, v137
	v_mul_f32_e32 v19, v19, v22
	v_bfe_u32 v22, v19, 16, 1
	v_add3_u32 v19, v19, v22, s21
	global_store_short_d16_hi v[20:21], v19, off offset:2048
	v_lshlrev_b32_e32 v19, 16, v143
	v_lshlrev_b32_e32 v20, 16, v144
	v_mul_f32_e32 v19, v19, v20
	v_mul_f32_e32 v20, v124, v18
	v_fmac_f32_e32 v20, v123, v139
	v_fmac_f32_e32 v20, v125, v19
	v_lshlrev_b32_e32 v21, 16, v136
	v_mul_f32_e32 v20, v20, v21
	v_bfe_u32 v21, v20, 16, 1
	v_add3_u32 v20, v20, v21, s21
	s_and_b32 s0, s36, s58
	global_store_short_d16_hi v[2:3], v20, off offset:2048
	v_lshlrev_b32_e32 v2, 16, v141
	v_lshlrev_b32_e32 v3, 16, v142
	s_cmp_lg_u32 s0, s58
	v_mul_f32_e32 v2, v2, v3
	s_cselect_b64 vcc, -1, 0
	v_mul_f32_e32 v3, v124, v19
	v_cndmask_b32_e32 v2, 0, v2, vcc
	v_fmac_f32_e32 v3, v123, v18
	v_fmac_f32_e32 v3, v125, v2
	v_lshlrev_b32_e32 v2, 16, v135
	v_mul_f32_e32 v2, v3, v2
	v_bfe_u32 v3, v2, 16, 1
	s_add_i32 s0, s60, 4
	v_add3_u32 v2, v2, v3, s21
	s_cmp_gt_u32 s60, 11
	s_mov_b32 s60, s0
	global_store_short_d16_hi v[0:1], v2, off offset:2048
	s_cbranch_scc0 .LBB0_94
	v_readlane_b32 s0, v240, 4
	v_readlane_b32 s1, v240, 5
	s_load_dword s0, s[0:1], 0x0
	s_movk_i32 s33, 0x3600
	s_waitcnt lgkmcnt(0)
	s_add_i32 s55, s0, s55
	s_cmp_ge_i32 s55, s72
	s_cbranch_scc0 .LBB0_90
